# attention: rope factors of a local K tile loaded one tile ahead into dead registers (v200-215)
# speedup vs baseline: 1.0037x; 1.0012x over previous
; __device__ __forceinline__ void attn_item_mfma(Frame& F, const Args& AR, int l, int item) {
;     ...
;     const int g = F.wave >> 1, wq = F.wave & 1, h = kv * 4 + g, r32 = F.lane & 31, hi = F.lane >> 5;
;     constexpr float C2 = 0.125f * 1.4426950408889634f;
;     const int qq = 32 * wq + r32;
;     const int qpos = n * 128 + 64 * hq + qq;
;     const int qrow = latent ? b * SEQ + qpos : R_LAT + b * CTXL + qpos;
;     bf16x8v qf[4];
;     {
;         const bf16* qp = P + (size_t)qrow * DIN + Q_OFF + h * 64 + 8 * hi;
;         float x[4][8];
; #pragma unroll
;         for (int ks = 0; ks < 4; ++ks) unpack8(*(const v4u*)(qp + 16 * ks), x[ks]);
;         if (latent) {
; #pragma unroll
;             for (int part = 0; part < 2; ++part) { const int pos = part ? (qpos & 63) : (qpos >> 6);
; #pragma unroll
;                 for (int t = 0; t < 8; ++t) { const f32x2 cs = *(const f32x2*)(rope + (pos * 16 + 8 * hi + t) * 2);
;                     const float x1 = x[2 * part][t], x2 = x[2 * part + 1][t]; x[2 * part][t] = x1 * cs.x - x2 * cs.y; x[2 * part + 1][t] = x2 * cs.x + x1 * cs.y; } }
;         }
; #pragma unroll
;         for (int ks = 0; ks < 4; ++ks) { v4u w; w.x = pk2(x[ks][0] * C2, x[ks][1] * C2); w.y = pk2(x[ks][2] * C2, x[ks][3] * C2); w.z = pk2(x[ks][4] * C2, x[ks][5] * C2); w.w = pk2(x[ks][6] * C2, x[ks][7] * C2);
;             qf[ks] = __builtin_bit_cast(bf16x8v, w); }
;     }
;     float mrun = AR.in[I_SINK][l * 8 + h] * 1.4426950408889634f, lsum = hi == 0 ? 1.0f : 0.0f;
;     f32x16 o[2];
; #pragma unroll
;     for (int db = 0; db < 2; ++db)
; #pragma unroll
;         for (int r = 0; r < 16; ++r) o[db][r] = 0.f;
;     int tlo = hq, thi = hq + 4;
;     if (latent) { if (n == 0 && tlo < 2) tlo = 2; if (n == 31 && thi > 3) thi = 3; } else { tlo = 0; thi = -1; }
;     const int nloc = thi - tlo + 1, ntile = nloc + 4;
;     const int sj = F.tid >> 3, sd0 = (F.tid & 7) * 8;
;     v4u kw, kp, vw;
;     { const bool lc = 0 < nloc; const int kp0 = lc ? 128 * (n - 1) + 64 * tlo : 0; const int krow = lc ? b * SEQ + kp0 + sj : R_LAT + b * CTXL + kp0 + sj;
;     ...
;         if (rel == 0 || rel == 4) {
; #pragma unroll
;             for (int kb = 0; kb < 2; ++kb)
; #pragma unroll
;                 for (int r = 0; r < 16; ++r) { const int kk = 32 * kb + crow16(r, hi); const bool bad = rel == 0 ? kk < qq : kk > qq; st[kb][r] = bad ? -1e30f : st[kb][r]; } }
.LBB0_1283:
	v_lshlrev_b32_e32 v35, 3, v70
	v_and_b32_e32 v34, 56, v35
	v_cmp_gt_u32_e64 s[14:15], 32, v34
	v_lshlrev_b32_e32 v103, 2, v48
	v_cmp_gt_u32_e32 vcc, 32, v149
	v_writelane_b32 v250, s14, 54
	v_bitop3_b32 v36, v35, 16, 56 bitop3:0x6c
	v_cndmask_b32_e64 v111, 0, 1.0, vcc
	v_writelane_b32 v250, s15, 55
	v_cmp_lt_u32_e64 s[14:15], v103, v46
	v_and_b32_e32 v35, 2, v70
	v_cmp_lt_i32_e32 vcc, v224, v218
	v_writelane_b32 v254, s14, 57
	v_cmp_eq_u32_e64 s[38:39], 0, v35
	v_cndmask_b32_e32 v35, v217, v224, vcc
	v_writelane_b32 v254, s15, 58
	v_cmp_gt_u32_e64 s[14:15], v103, v46
	v_lshlrev_b32_e32 v107, 2, v35
	v_or_b32_e32 v35, 1, v103
	v_writelane_b32 v254, s14, 59
	s_or_b32 s10, s6, 4
	v_ashrrev_i32_e32 v104, 3, v70
	v_writelane_b32 v254, s15, 60
	v_cmp_lt_u32_e64 s[14:15], v35, v46
	v_or_b32_e32 v35, 2, v103
	s_movk_i32 s11, 0x90
	v_writelane_b32 v254, s14, 61
	v_mul_lo_u32 v105, v104, s11
	v_lshlrev_b32_e32 v57, 4, v70
	v_writelane_b32 v254, s15, 62
	v_cmp_ge_u32_e64 s[14:15], v103, v46
	v_lshlrev_b32_e32 v98, 1, v34
	v_mov_b32_e32 v99, v195
	v_writelane_b32 v254, s14, 63
	v_lshlrev_b32_e32 v194, 1, v36
	v_readlane_b32 s11, v254, 53
	v_writelane_b32 v255, s15, 0
	v_cmp_lt_u32_e64 s[14:15], v35, v46
	v_mul_u32_u24_e32 v109, 0x90, v47
	v_or_b32_e32 v37, 26, v103
	v_writelane_b32 v255, s14, 1
	v_or_b32_e32 v38, 27, v103
	v_or_b32_e32 v39, 32, v103
	v_writelane_b32 v255, s15, 2
	v_cmp_gt_u32_e64 s[14:15], v35, v46
	v_or_b32_e32 v35, 3, v103
	v_or_b32_e32 v40, 33, v103
	v_writelane_b32 v255, s14, 3
	v_or_b32_e32 v41, 34, v103
	v_or_b32_e32 v42, 35, v103
	v_writelane_b32 v255, s15, 4
	v_cmp_lt_u32_e64 s[14:15], v35, v46
	v_or_b32_e32 v43, 40, v103
	v_or_b32_e32 v44, 41, v103
	v_writelane_b32 v255, s14, 5
	v_or_b32_e32 v45, 42, v103
	v_or_b32_e32 v47, 43, v103
	v_writelane_b32 v255, s15, 6
	v_cmp_gt_u32_e64 s[14:15], v35, v46
	v_or_b32_e32 v35, 8, v103
	v_or_b32_e32 v48, 48, v103
	v_writelane_b32 v255, s14, 7
	v_or_b32_e32 v49, 49, v103
	v_or_b32_e32 v50, 50, v103
	v_writelane_b32 v255, s15, 8
	v_cmp_lt_u32_e64 s[14:15], v35, v46
	v_or_b32_e32 v51, 51, v103
	v_or_b32_e32 v52, 56, v103
	v_writelane_b32 v255, s14, 9
	v_or_b32_e32 v54, 57, v103
	v_or_b32_e32 v55, 58, v103
	v_writelane_b32 v255, s15, 10
	v_cmp_gt_u32_e64 s[14:15], v35, v46
	v_or_b32_e32 v35, 9, v103
	v_or_b32_e32 v56, 59, v103
	v_writelane_b32 v255, s14, 11
	v_ashrrev_i32_e32 v95, 31, v94
	s_mov_b32 s84, 0
	v_writelane_b32 v255, s15, 12
	v_cmp_lt_u32_e64 s[14:15], v35, v46
	v_lshlrev_b32_e32 v106, 1, v104
	v_mul_u32_u24_e32 v108, 0x90, v34
	v_writelane_b32 v255, s14, 13
	v_and_b32_e32 v110, 16, v57
	v_lshlrev_b32_e32 v100, 1, v36
	v_writelane_b32 v255, s15, 14
	v_cmp_gt_u32_e64 s[14:15], v35, v46
	v_or_b32_e32 v35, 10, v103
	v_cmp_lt_u32_e64 s[76:77], v37, v46
	v_writelane_b32 v255, s14, 15
	v_cmp_lt_u32_e64 s[18:19], v41, v46
	v_cmp_gt_u32_e64 s[20:21], v41, v46
	v_writelane_b32 v255, s15, 16
	v_cmp_lt_u32_e64 s[14:15], v35, v46
	v_cmp_lt_u32_e64 s[22:23], v42, v46
	v_cmp_lt_u32_e64 s[26:27], v43, v46
	v_writelane_b32 v255, s14, 17
	v_cmp_gt_u32_e64 s[28:29], v43, v46
	v_cmp_lt_u32_e64 s[30:31], v44, v46
	v_writelane_b32 v255, s15, 18
	v_cmp_gt_u32_e64 s[14:15], v35, v46
	v_or_b32_e32 v35, 11, v103
	v_cmp_gt_u32_e64 s[34:35], v44, v46
	v_writelane_b32 v255, s14, 19
	v_cmp_gt_u32_e64 s[36:37], v45, v46
	v_cmp_lt_u32_e64 s[40:41], v47, v46
	v_writelane_b32 v255, s15, 20
	v_cmp_lt_u32_e64 s[14:15], v35, v46
	v_cmp_gt_u32_e64 s[42:43], v47, v46
	v_cmp_lt_u32_e64 s[44:45], v48, v46
	v_writelane_b32 v255, s14, 21
	v_cmp_gt_u32_e64 s[46:47], v48, v46
	v_cmp_lt_u32_e64 s[48:49], v49, v46
	v_writelane_b32 v255, s15, 22
	v_cmp_gt_u32_e64 s[14:15], v35, v46
	v_or_b32_e32 v35, 16, v103
	v_cmp_gt_u32_e64 s[50:51], v49, v46
	v_writelane_b32 v255, s14, 23
	v_cmp_lt_u32_e64 s[52:53], v50, v46
	v_cmp_gt_u32_e64 s[54:55], v50, v46
	v_writelane_b32 v255, s15, 24
	v_cmp_lt_u32_e64 s[14:15], v35, v46
	v_cmp_lt_u32_e64 s[56:57], v51, v46
	v_cmp_gt_u32_e64 s[58:59], v51, v46
	v_writelane_b32 v255, s14, 25
	v_cmp_lt_u32_e64 s[60:61], v52, v46
	v_cmp_gt_u32_e64 s[62:63], v52, v46
	v_writelane_b32 v255, s15, 26
	v_cmp_gt_u32_e64 s[14:15], v35, v46
	v_or_b32_e32 v35, 17, v103
	v_cmp_lt_u32_e64 s[64:65], v54, v46
	v_writelane_b32 v255, s14, 27
	v_cmp_gt_u32_e64 s[66:67], v54, v46
	v_cmp_lt_u32_e64 s[68:69], v55, v46
	v_writelane_b32 v255, s15, 28
	v_cmp_lt_u32_e64 s[14:15], v35, v46
	v_cmp_lt_u32_e64 s[72:73], v56, v46
	v_cmp_gt_u32_e64 s[74:75], v56, v46
	v_writelane_b32 v255, s14, 29
	s_nop 1
	v_writelane_b32 v255, s15, 30
	v_cmp_gt_u32_e64 s[14:15], v35, v46
	v_or_b32_e32 v35, 18, v103
	s_nop 0
	v_writelane_b32 v255, s14, 31
	s_nop 1
	v_writelane_b32 v255, s15, 32
	v_cmp_lt_u32_e64 s[14:15], v35, v46
	s_nop 1
	v_writelane_b32 v255, s14, 33
	s_nop 1
	v_writelane_b32 v255, s15, 34
	v_cmp_gt_u32_e64 s[14:15], v35, v46
	v_or_b32_e32 v35, 19, v103
	s_nop 0
	v_writelane_b32 v255, s14, 35
	s_nop 1
	v_writelane_b32 v255, s15, 36
	v_cmp_lt_u32_e64 s[14:15], v35, v46
	s_nop 1
	v_writelane_b32 v255, s14, 37
	s_nop 1
	v_writelane_b32 v255, s15, 38
	v_cmp_gt_u32_e64 s[14:15], v35, v46
	v_or_b32_e32 v35, 24, v103
	s_nop 0
	v_writelane_b32 v255, s14, 39
	s_nop 1
	v_writelane_b32 v255, s15, 40
	v_cmp_lt_u32_e64 s[14:15], v35, v46
	s_nop 1
	v_writelane_b32 v255, s14, 41
	s_nop 1
	v_writelane_b32 v255, s15, 42
	v_cmp_gt_u32_e64 s[14:15], v35, v46
; __device__ __forceinline__ unsigned pk2(float lo, float hi) { const f32x2cv v = {lo, hi}; return __builtin_bit_cast(unsigned, __builtin_convertvector(v, bf16x2cv)); }
; __device__ __forceinline__ void attn_item_mfma(Frame& F, const Args& AR, int l, int item) {
;     ...
; #pragma unroll
;         for (int ks = 0; ks < 4; ++ks) { v4u w; w.x = pk2(x[ks][0] * C2, x[ks][1] * C2); w.y = pk2(x[ks][2] * C2, x[ks][3] * C2); w.z = pk2(x[ks][4] * C2, x[ks][5] * C2); w.w = pk2(x[ks][6] * C2, x[ks][7] * C2);
;             qf[ks] = __builtin_bit_cast(bf16x8v, w); }
;     }
;     float mrun = AR.in[I_SINK][l * 8 + h] * 1.4426950408889634f, lsum = hi == 0 ? 1.0f : 0.0f;
;     f32x16 o[2];
; #pragma unroll
;     for (int db = 0; db < 2; ++db)
; #pragma unroll
;         for (int r = 0; r < 16; ++r) o[db][r] = 0.f;
;     int tlo = hq, thi = hq + 4;
;     if (latent) { if (n == 0 && tlo < 2) tlo = 2; if (n == 31 && thi > 3) thi = 3; } else { tlo = 0; thi = -1; }
;     const int nloc = thi - tlo + 1, ntile = nloc + 4;
;     const int sj = F.tid >> 3, sd0 = (F.tid & 7) * 8;
;     v4u kw, kp, vw;
;     { const bool lc = 0 < nloc; const int kp0 = lc ? 128 * (n - 1) + 64 * tlo : 0; const int krow = lc ? b * SEQ + kp0 + sj : R_LAT + b * CTXL + kp0 + sj;
;       const bf16* kp_ = P + (size_t)krow * DIN + K_OFF + kv * 64; kw = *(const v4u*)(kp_ + sd0); kp = *(const v4u*)(kp_ + (sd0 ^ 16)); vw = *(const v4u*)(P + (size_t)krow * DIN + V_OFF + kv * 64 + sd0); }
;     __syncthreads();
;     ...
;             if (local) { const int kpos = kpos0 + sj, part = sd0 >> 5, e0 = sd0 & 31; const bool firsth = e0 < 16; const int pp = part ? (kpos & 63) : (kpos >> 6);
; #pragma unroll
;                 for (int t = 0; t < 8; ++t) { const f32x2 cs = *(const f32x2*)(rope + (pp * 16 + (e0 & 15) + t) * 2); kk[t] = firsth ? kk[t] * cs.x - kq[t] * cs.y : kk[t] * cs.x + kq[t] * cs.y; } }
	v_or_b32_e32 v35, 25, v103
	v_cmp_lt_u32_e64 s[94:95], v35, v46
	v_writelane_b32 v255, s14, 43
	v_cmp_gt_u32_e64 s[96:97], v35, v46
	s_nop 0
	v_writelane_b32 v255, s15, 44
	s_and_b64 s[14:15], s[0:1], exec
	s_cselect_b32 s9, s12, s9
	s_add_i32 s12, s5, s11
	s_ashr_i32 s13, s12, 31
	s_lshl_b64 s[12:13], s[12:13], 2
	s_add_u32 s12, s70, s12
	s_addc_u32 s13, s71, s13
	global_load_dword v53, v195, s[12:13]
	s_mov_b32 s12, 0x3e38aa3b
	v_pk_mul_f32 v[2:3], v[2:3], s[12:13] op_sel_hi:[1,0]
	s_cmp_lg_u32 s8, 0
	v_pk_mov_b32 v[2:3], v[2:3], v[2:3] op_sel:[1,0]
	s_cselect_b32 s5, s6, 2
	v_cvt_pk_bf16_f32 v69, v2, v3
	v_pk_mul_f32 v[2:3], v[18:19], s[12:13] op_sel_hi:[1,0]
	s_cmp_lg_u32 s8, 31
	v_pk_mov_b32 v[2:3], v[2:3], v[2:3] op_sel:[1,0]
	s_cselect_b32 s8, s10, 3
	v_cvt_pk_bf16_f32 v70, v2, v3
	v_pk_mul_f32 v[2:3], v[20:21], s[12:13] op_sel_hi:[1,0]
	s_and_b64 s[0:1], s[0:1], exec
	v_pk_mov_b32 v[2:3], v[2:3], v[2:3] op_sel:[1,0]
	v_pk_mul_f32 v[8:9], v[8:9], s[12:13] op_sel_hi:[1,0]
	v_cvt_pk_bf16_f32 v71, v2, v3
	v_pk_mul_f32 v[2:3], v[22:23], s[12:13] op_sel_hi:[1,0]
	v_pk_mul_f32 v[6:7], v[6:7], s[12:13] op_sel_hi:[1,0]
	v_pk_mov_b32 v[2:3], v[2:3], v[2:3] op_sel:[1,0]
	v_pk_mul_f32 v[4:5], v[4:5], s[12:13] op_sel_hi:[1,0]
	v_cvt_pk_bf16_f32 v72, v2, v3
	v_pk_mul_f32 v[2:3], v[24:25], s[12:13] op_sel_hi:[1,0]
	s_cselect_b32 s8, s8, -1
	v_pk_mov_b32 v[2:3], v[2:3], v[2:3] op_sel:[1,0]
	v_readlane_b32 s10, v252, 60
	v_cvt_pk_bf16_f32 v73, v2, v3
	v_pk_mul_f32 v[2:3], v[32:33], s[12:13] op_sel_hi:[1,0]
	v_pk_mov_b32 v[4:5], v[4:5], v[4:5] op_sel:[1,0]
	v_cvt_pk_bf16_f32 v74, v2, v3
	v_pk_mul_f32 v[2:3], v[30:31], s[12:13] op_sel_hi:[1,0]
	v_readlane_b32 s11, v252, 61
	v_cvt_pk_bf16_f32 v75, v2, v3
	v_pk_mul_f32 v[2:3], v[28:29], s[12:13] op_sel_hi:[1,0]
	s_cselect_b32 s13, s5, 0
	s_sub_i32 s85, s8, s13
	s_not_b32 s0, s85
	s_lshl_b32 s5, s13, 6
	v_writelane_b32 v255, s0, 45
	s_add_i32 s0, s7, s5
	s_lshl_b32 s1, s9, 12
	s_lshl_b32 s87, s9, 8
	s_add_i32 s88, s0, 0xffffff80
	s_addk_i32 s87, 0x2000
	s_add_i32 s0, s88, s1
	s_cmp_lt_i32 s85, 0
	s_cselect_b32 s0, s87, s0
	v_cvt_pk_bf16_f32 v68, v4, v5
	v_cvt_pk_bf16_f32 v76, v2, v3
	v_add_u32_e32 v4, s0, v104
	v_mov_b64_e32 v[2:3], s[10:11]
	v_writelane_b32 v255, s1, 46
	v_mad_i64_i32 v[2:3], s[0:1], v4, s25, v[2:3]
	s_lshl_b32 s16, s4, 7
	v_lshl_add_u64 v[2:3], v[2:3], 0, s[16:17]
	v_lshl_add_u64 v[4:5], v[2:3], 0, v[98:99]
	v_lshl_add_u64 v[2:3], v[2:3], 0, v[194:195]
	global_load_dwordx4 v[82:85], v[2:3], off
	global_load_dwordx4 v[86:89], v[4:5], off
	global_load_dwordx4 v[90:93], v[4:5], off offset:256
	v_pk_mul_f32 v[2:3], v[26:27], s[12:13] op_sel_hi:[1,0]
	s_sub_i32 s0, s7, 64
	v_cvt_pk_bf16_f32 v77, v2, v3
	v_pk_mul_f32 v[2:3], v[10:11], s[12:13] op_sel_hi:[1,0]
	s_add_i32 s89, s85, 4
	v_cvt_pk_bf16_f32 v78, v2, v3
	v_pk_mul_f32 v[2:3], v[12:13], s[12:13] op_sel_hi:[1,0]
	v_pk_mov_b32 v[8:9], v[8:9], v[8:9] op_sel:[1,0]
	v_cvt_pk_bf16_f32 v79, v2, v3
	v_pk_mul_f32 v[2:3], v[14:15], s[12:13] op_sel_hi:[1,0]
	v_pk_mov_b32 v[6:7], v[6:7], v[6:7] op_sel:[1,0]
	v_cvt_pk_bf16_f32 v80, v2, v3
	v_pk_mul_f32 v[2:3], v[16:17], s[12:13] op_sel_hi:[1,0]
	v_writelane_b32 v250, s16, 58
	s_add_u32 s80, s10, s16
	v_mov_b32_e32 v16, v195
	v_mov_b32_e32 v17, v195
	v_cvt_pk_bf16_f32 v66, v8, v9
	v_cvt_pk_bf16_f32 v67, v6, v7
	v_cvt_pk_bf16_f32 v81, v2, v3
	v_writelane_b32 v255, s0, 47
	s_addc_u32 s81, s11, 0
	s_lshl_b32 s0, s8, 6
	v_mov_b32_e32 v2, v195
	v_mov_b32_e32 v3, v195
	v_mov_b32_e32 v4, v195
	v_mov_b32_e32 v5, v195
	v_mov_b32_e32 v6, v195
	v_mov_b32_e32 v7, v195
	v_mov_b32_e32 v8, v195
	v_mov_b32_e32 v9, v195
	v_mov_b32_e32 v10, v195
	v_mov_b32_e32 v11, v195
	v_mov_b32_e32 v12, v195
	v_mov_b32_e32 v13, v195
	v_mov_b32_e32 v14, v195
	v_mov_b32_e32 v15, v195
	v_mov_b64_e32 v[32:33], v[16:17]
	s_waitcnt vmcnt(3)
	v_mul_f32_e32 v99, 0x3fb8aa3b, v53
	v_writelane_b32 v250, s17, 59
	s_sub_i32 s90, s5, s0
	s_add_i32 s91, s85, 5
	v_writelane_b32 v255, s13, 48
	s_sub_i32 s92, s13, s6
	v_lshlrev_b32_e32 v194, 1, v34
	v_mov_b64_e32 v[30:31], v[14:15]
	v_mov_b64_e32 v[28:29], v[12:13]
	v_mov_b64_e32 v[26:27], v[10:11]
	v_mov_b64_e32 v[24:25], v[8:9]
	v_mov_b64_e32 v[22:23], v[6:7]
	v_mov_b64_e32 v[20:21], v[4:5]
	v_mov_b64_e32 v[18:19], v[2:3]
	v_cmp_gt_u32_e64 s[4:5], v37, v46
	v_cmp_lt_u32_e64 s[6:7], v38, v46
	v_cmp_gt_u32_e64 s[8:9], v38, v46
	v_cmp_lt_u32_e64 s[10:11], v39, v46
	v_cmp_gt_u32_e64 s[12:13], v39, v46
	v_cmp_lt_u32_e64 s[14:15], v40, v46
	v_cmp_ge_u32_e64 s[16:17], v39, v46
	v_cmp_gt_u32_e64 s[24:25], v42, v46
	v_cmp_lt_u32_e64 s[0:1], v45, v46
	v_cmp_gt_u32_e64 s[70:71], v55, v46
	s_cmp_lt_i32 s85, 0
	s_cbranch_scc1 .Lattn_norope0
	v_add_u32_e32 v212, s88, v104
	v_and_b32_e32 v213, 4, v0
	v_lshrrev_b32_e32 v214, 1, v213
	v_add_u32_e32 v213, v213, v214
	v_sub_u32_e32 v213, 6, v213
	v_lshrrev_b32_e32 v212, v213, v212
	v_and_b32_e32 v212, 63, v212
	v_lshl_or_b32 v212, v212, 5, v110
	v_mov_b32_e32 v213, 0
	v_readlane_b32 s98, v253, 11
	s_nop 1
	v_mov_b32_e32 v214, s98
	v_readlane_b32 s98, v253, 12
	s_nop 1
	v_mov_b32_e32 v215, s98
	v_lshl_add_u64 v[214:215], v[212:213], 2, v[214:215]
	global_load_dwordx4 v[200:203], v[214:215], off
	global_load_dwordx4 v[204:207], v[214:215], off offset:16
	global_load_dwordx4 v[208:211], v[214:215], off offset:32
	s_nop 0
	global_load_dwordx4 v[212:215], v[214:215], off offset:48
.Lattn_norope0:
	s_barrier

; __device__ __forceinline__ void unpack8(const v4u w, float (&x)[8]) { x[0] = bflo(w.x); x[1] = bfhi(w.x); x[2] = bflo(w.y); x[3] = bfhi(w.y); x[4] = bflo(w.z); x[5] = bfhi(w.z); x[6] = bflo(w.w); x[7] = bfhi(w.w); }
; __device__ __forceinline__ void attn_item_mfma(Frame& F, const Args& AR, int l, int item) {
;     ...
;             float kk[8], kq[8], vv[8]; unpack8(kw, kk); unpack8(kp, kq); unpack8(vw, vv);
;             if (local) { const int kpos = kpos0 + sj, part = sd0 >> 5, e0 = sd0 & 31; const bool firsth = e0 < 16; const int pp = part ? (kpos & 63) : (kpos >> 6);
; #pragma unroll
;                 for (int t = 0; t < 8; ++t) { const f32x2 cs = *(const f32x2*)(rope + (pp * 16 + (e0 & 15) + t) * 2); kk[t] = firsth ? kk[t] * cs.x - kq[t] * cs.y : kk[t] * cs.x + kq[t] * cs.y; } }
.LBB0_1286:
	s_waitcnt vmcnt(0)
	v_lshlrev_b32_e32 v41, 16, v86
	v_and_b32_e32 v40, 0xffff0000, v86
	v_lshlrev_b32_e32 v39, 16, v87
	v_and_b32_e32 v38, 0xffff0000, v87
	v_lshlrev_b32_e32 v37, 16, v88
	v_and_b32_e32 v36, 0xffff0000, v88
	v_lshlrev_b32_e32 v34, 16, v89
	s_andn2_b64 vcc, exec, s[82:83]
	v_and_b32_e32 v35, 0xffff0000, v89
	s_cbranch_vccnz .LBB0_1288
	v_and_b32_e32 v58, 0xffff0000, v85
	v_lshlrev_b32_e32 v59, 16, v85
	v_and_b32_e32 v60, 0xffff0000, v84
	v_lshlrev_b32_e32 v61, 16, v84
	v_and_b32_e32 v62, 0xffff0000, v83
	v_lshlrev_b32_e32 v63, 16, v83
	v_and_b32_e32 v64, 0xffff0000, v82
	v_lshlrev_b32_e32 v65, 16, v82
	v_mul_f32_e32 v201, v201, v65
	v_mul_f32_e32 v203, v203, v64
	v_mul_f32_e32 v205, v205, v63
	v_mul_f32_e32 v207, v207, v62
	v_mul_f32_e32 v209, v209, v61
	v_mul_f32_e32 v211, v211, v60
	v_mul_f32_e32 v213, v213, v59
	v_mul_f32_e32 v215, v215, v58
	v_cndmask_b32_e64 v201, v201, -v201, s[38:39]
	v_cndmask_b32_e64 v203, v203, -v203, s[38:39]
	v_cndmask_b32_e64 v205, v205, -v205, s[38:39]
	v_cndmask_b32_e64 v207, v207, -v207, s[38:39]
	v_cndmask_b32_e64 v209, v209, -v209, s[38:39]
	v_cndmask_b32_e64 v211, v211, -v211, s[38:39]
	v_cndmask_b32_e64 v213, v213, -v213, s[38:39]
	v_cndmask_b32_e64 v215, v215, -v215, s[38:39]
	v_fmac_f32_e32 v201, v200, v41
	v_fmac_f32_e32 v203, v202, v40
	v_fmac_f32_e32 v205, v204, v39
	v_fmac_f32_e32 v207, v206, v38
	v_fmac_f32_e32 v209, v208, v37
	v_fmac_f32_e32 v211, v210, v36
	v_fmac_f32_e32 v213, v212, v34
	v_fmac_f32_e32 v215, v214, v35
	v_mov_b32_e32 v35, v215
	v_mov_b32_e32 v34, v213
	v_mov_b32_e32 v36, v211
	v_mov_b32_e32 v37, v209
	v_mov_b32_e32 v38, v207
	v_mov_b32_e32 v39, v205
	v_mov_b32_e32 v40, v203
	v_mov_b32_e32 v41, v201

; #define LAS __attribute__((address_space(3)))
; __device__ __forceinline__ void attn_item_mfma(Frame& F, const Args& AR, int l, int item) {
;     ...
;         if (s + 1 < ntile) { const bool lc = s + 1 < nloc; const int kp0 = lc ? 128 * (n - 1) + 64 * (tlo + s + 1) : 64 * (s + 1 - nloc); const int krow = lc ? b * SEQ + kp0 + sj : R_LAT + b * CTXL + kp0 + sj;
;             const bf16* kp_ = P + (size_t)krow * DIN + K_OFF + kv * 64; kw = *(const v4u*)(kp_ + sd0); kp = *(const v4u*)(kp_ + (sd0 ^ 16)); vw = *(const v4u*)(P + (size_t)krow * DIN + V_OFF + kv * 64 + sd0); }
;         const int rel = local ? (tlo + s) - hq : 2;
;         f32x16 st[2];
; #pragma unroll
;         for (int kb = 0; kb < 2; ++kb) {
; #pragma unroll
;             for (int r = 0; r < 16; ++r) st[kb][r] = 0.f;
; #pragma unroll
;             for (int ks = 0; ks < 4; ++ks) { const bf16x8v kf = *(const LAS bf16x8v*)(kb_ + (32 * kb + r32) * AT_ROW + (16 * ks + 8 * hi) * 2);
;                 st[kb] = __builtin_amdgcn_mfma_f32_32x32x16_bf16(kf, qf[ks], st[kb], 0, 0, 0); }
;         }
;     ...
;             for (int db = 0; db < 2; ++db) { const LAS unsigned char* vp = vb_ + (32 * db + r32) * AT_ROW + (16 * m + 4 * hi) * 2;
;                 const v2u lo = *(const LAS v2u*)vp, hh = *(const LAS v2u*)(vp + 16); const v4u w = {lo.x, lo.y, hh.x, hh.y};
.LBB0_1291:
	s_add_i32 s82, s83, s82
	s_nop 0
	v_add_u32_e32 v36, s82, v104
	v_mov_b64_e32 v[34:35], s[80:81]
	s_movk_i32 s82, 0x1600
	v_mad_i64_i32 v[34:35], s[82:83], v36, s82, v[34:35]
	v_mov_b32_e32 v101, v195
	v_lshl_add_u64 v[36:37], v[34:35], 0, v[194:195]
	v_lshl_add_u64 v[34:35], v[34:35], 0, v[100:101]
	global_load_dwordx4 v[82:85], v[34:35], off
	global_load_dwordx4 v[86:89], v[36:37], off
	global_load_dwordx4 v[90:93], v[36:37], off offset:256
	s_cmp_ge_i32 s84, s85
	s_cbranch_scc1 .Lattn_norope1
	s_add_i32 s98, s88, 64
	s_nop 0
	v_add_u32_e32 v212, s98, v104
	v_and_b32_e32 v213, 4, v0
	v_lshrrev_b32_e32 v214, 1, v213
	v_add_u32_e32 v213, v213, v214
	v_sub_u32_e32 v213, 6, v213
	v_lshrrev_b32_e32 v212, v213, v212
	v_and_b32_e32 v212, 63, v212
	v_lshl_or_b32 v212, v212, 5, v110
	v_mov_b32_e32 v213, 0
	v_readlane_b32 s98, v253, 11
	s_nop 1
	v_mov_b32_e32 v214, s98
	v_readlane_b32 s98, v253, 12
	s_nop 1
	v_mov_b32_e32 v215, s98
	v_lshl_add_u64 v[214:215], v[212:213], 2, v[214:215]
	global_load_dwordx4 v[200:203], v[214:215], off
	global_load_dwordx4 v[204:207], v[214:215], off offset:16
	global_load_dwordx4 v[208:211], v[214:215], off offset:32
	s_nop 0
	global_load_dwordx4 v[212:215], v[214:215], off offset:48
.Lattn_norope1:
.LBB0_1292:
	v_add3_u32 v101, s93, v96, v109
	ds_read_b128 v[124:127], v101
	ds_read_b128 v[128:131], v101 offset:32
	ds_read_b128 v[132:135], v101 offset:64
	ds_read_b128 v[136:139], v101 offset:96
	ds_read_b128 v[140:143], v101 offset:4608
	ds_read_b128 v[144:147], v101 offset:4640
	ds_read_b128 v[150:153], v101 offset:4672
	ds_read_b128 v[154:157], v101 offset:4704
	s_add_i32 s82, s92, s84
	s_and_b64 s[78:79], s[78:79], exec
	s_cselect_b32 s86, 2, s82
	s_cmp_lt_i32 s86, 4
	s_waitcnt lgkmcnt(7)
	v_mfma_f32_32x32x16_bf16 v[50:65], v[124:127], v[66:69], 0
	s_waitcnt lgkmcnt(6)
	v_mfma_f32_32x32x16_bf16 v[50:65], v[128:131], v[70:73], v[50:65]
	s_waitcnt lgkmcnt(5)
	v_mfma_f32_32x32x16_bf16 v[50:65], v[132:135], v[74:77], v[50:65]
	s_waitcnt lgkmcnt(4)
	v_mfma_f32_32x32x16_bf16 v[50:65], v[136:139], v[78:81], v[50:65]
	s_waitcnt lgkmcnt(3)
	v_mfma_f32_32x32x16_bf16 v[34:49], v[140:143], v[66:69], 0
	s_waitcnt lgkmcnt(2)
	v_mfma_f32_32x32x16_bf16 v[34:49], v[144:147], v[70:73], v[34:49]
	s_waitcnt lgkmcnt(1)
	v_mfma_f32_32x32x16_bf16 v[34:49], v[150:153], v[74:77], v[34:49]
	s_waitcnt lgkmcnt(0)
	v_mfma_f32_32x32x16_bf16 v[34:49], v[154:157], v[78:81], v[34:49]
	v_add3_u32 v190, s93, v97, v109
	v_add_u32_e32 v191, 0x3000, v190
	v_add_u32_e32 v190, 0x2000, v190
	ds_read2_b64 v[158:161], v190 offset0:128 offset1:130
	ds_read2_b64 v[162:165], v190 offset0:132 offset1:134
	ds_read2_b64 v[166:169], v191 offset0:192 offset1:194
	ds_read2_b64 v[170:173], v191 offset0:196 offset1:198
	ds_read2_b64 v[174:177], v190 offset0:136 offset1:138
	ds_read2_b64 v[178:181], v191 offset0:200 offset1:202
	ds_read2_b64 v[182:185], v190 offset0:140 offset1:142
	ds_read2_b64 v[186:189], v191 offset0:204 offset1:206
	s_cbranch_scc1 .LBB0_1294
	s_cmp_eq_u32 s86, 4
	s_cselect_b64 s[78:79], -1, 0
	s_cbranch_execz .LBB0_1295
	s_branch .LBB0_1296
